# emission split: QD half in waves 4-7's idle time of step 5, KDT half in the T21 slot
# baseline (speedup 1.0000x reference)
.LBB0_206:
	s_add_i32 s6, s48, -4
	v_lshlrev_b32_e32 v2, 9, v94
	v_lshlrev_b32_e32 v3, 2, v94
	s_lshl_b32 s7, s6, 6
	v_lshl_add_u32 v2, v95, 4, v2
	v_add_u32_e32 v3, 0x24b00, v3
	v_add_u32_e32 v2, s7, v2
	s_lshl_b32 s7, s6, 10
	s_add_i32 s7, s7, s51
	v_lshl_add_u32 v9, v93, 4, s7
	ds_read_b32 v182, v3
	ds_read_b32 v184, v3 offset:128
	ds_read_b128 v[150:153], v2
	ds_read_b128 v[154:157], v2 offset:32
	ds_read_b128 v[158:161], v2 offset:256
	ds_read_b128 v[162:165], v2 offset:288
	ds_read_b128 v[166:169], v2 offset:16384
	ds_read_b128 v[170:173], v2 offset:16416
	ds_read_b128 v[174:177], v2 offset:16640
	ds_read_b128 v[178:181], v2 offset:16672
	s_waitcnt lgkmcnt(6)
	v_pk_mul_f32 v[150:151], v[150:151], v[182:183] op_sel_hi:[1,0]
	v_pk_mul_f32 v[152:153], v[152:153], v[182:183] op_sel_hi:[1,0]
	v_pk_mul_f32 v[154:155], v[154:155], v[182:183] op_sel_hi:[1,0]
	v_pk_mul_f32 v[156:157], v[156:157], v[182:183] op_sel_hi:[1,0]
	v_cvt_pk_bf16_f32 v10, v150, v151
	v_cvt_pk_bf16_f32 v11, v152, v153
	v_cvt_pk_bf16_f32 v12, v154, v155
	v_cvt_pk_bf16_f32 v13, v156, v157
	v_add_u32_e32 v6, 0x4000, v9
	buffer_store_dwordx4 v[10:13], v6, s[72:75], 0 offen sc1
	s_waitcnt lgkmcnt(4)
	v_pk_mul_f32 v[158:159], v[158:159], v[182:183] op_sel_hi:[1,0]
	v_pk_mul_f32 v[160:161], v[160:161], v[182:183] op_sel_hi:[1,0]
	v_pk_mul_f32 v[162:163], v[162:163], v[182:183] op_sel_hi:[1,0]
	v_pk_mul_f32 v[164:165], v[164:165], v[182:183] op_sel_hi:[1,0]
	v_cvt_pk_bf16_f32 v14, v158, v159
	v_cvt_pk_bf16_f32 v15, v160, v161
	v_cvt_pk_bf16_f32 v16, v162, v163
	v_cvt_pk_bf16_f32 v17, v164, v165
	v_add_u32_e32 v7, 0x5000, v9
	buffer_store_dwordx4 v[14:17], v7, s[72:75], 0 offen sc1
	s_waitcnt lgkmcnt(2)
	v_pk_mul_f32 v[166:167], v[166:167], v[184:185] op_sel_hi:[1,0]
	v_pk_mul_f32 v[168:169], v[168:169], v[184:185] op_sel_hi:[1,0]
	v_pk_mul_f32 v[170:171], v[170:171], v[184:185] op_sel_hi:[1,0]
	v_pk_mul_f32 v[172:173], v[172:173], v[184:185] op_sel_hi:[1,0]
	v_cvt_pk_bf16_f32 v18, v166, v167
	v_cvt_pk_bf16_f32 v19, v168, v169
	v_cvt_pk_bf16_f32 v20, v170, v171
	v_cvt_pk_bf16_f32 v21, v172, v173
	v_add_u32_e32 v6, 0x6000, v9
	buffer_store_dwordx4 v[18:21], v6, s[72:75], 0 offen sc1
	s_waitcnt lgkmcnt(0)
	v_pk_mul_f32 v[174:175], v[174:175], v[184:185] op_sel_hi:[1,0]
	v_pk_mul_f32 v[176:177], v[176:177], v[184:185] op_sel_hi:[1,0]
	v_pk_mul_f32 v[178:179], v[178:179], v[184:185] op_sel_hi:[1,0]
	v_pk_mul_f32 v[180:181], v[180:181], v[184:185] op_sel_hi:[1,0]
	v_cvt_pk_bf16_f32 v26, v174, v175
	v_cvt_pk_bf16_f32 v27, v176, v177
	v_cvt_pk_bf16_f32 v28, v178, v179
	v_cvt_pk_bf16_f32 v29, v180, v181
	v_add_u32_e32 v7, 0x7000, v9
	buffer_store_dwordx4 v[26:29], v7, s[72:75], 0 offen sc1

.LBB0_236:
	v_lshlrev_b32_e32 v88, 3, v95
	s_cmp_eq_u32 s48, 0
	v_or_b32_e32 v89, 16, v88
	s_waitcnt lgkmcnt(0)
	s_barrier
	s_cbranch_scc1 .LBB0_245
	s_cmp_gt_u32 s48, 3
	s_cbranch_scc0 .Lem_skip
	s_add_i32 s6, s48, -4
	v_lshlrev_b32_e32 v4, 11, v95
	v_lshlrev_b32_e32 v8, 4, v95
	s_lshl_b32 s7, s6, 6
	v_lshl_add_u32 v4, v94, 2, v4
	v_add_u32_e32 v8, s7, v8
	s_lshl_b32 s7, s6, 13
	s_add_i32 s7, s7, 0x8000
	v_add_u32_e32 v8, 0x24c00, v8
	v_add_u32_e32 v4, s7, v4
	s_lshl_b32 s7, s6, 10
	s_add_i32 s7, s7, s51
	v_add_u32_e32 v5, 0x80, v4
	v_lshl_add_u32 v9, v93, 4, s7
	ds_read_b128 v[186:189], v8
	ds_read_b128 v[190:193], v8 offset:32
	ds_read2st64_b32 v[194:195], v4 offset1:2
	ds_read2st64_b32 v[196:197], v4 offset0:4 offset1:6
	ds_read2st64_b32 v[198:199], v4 offset0:16 offset1:18
	ds_read2st64_b32 v[200:201], v4 offset0:20 offset1:22
	ds_read2st64_b32 v[202:203], v5 offset1:2
	ds_read2st64_b32 v[204:205], v5 offset0:4 offset1:6
	ds_read2st64_b32 v[206:207], v5 offset0:16 offset1:18
	ds_read2st64_b32 v[208:209], v5 offset0:20 offset1:22
	s_waitcnt lgkmcnt(4)
	ds_read2st64_b32 v[210:211], v4 offset0:1 offset1:3
	ds_read2st64_b32 v[212:213], v4 offset0:5 offset1:7
	ds_read2st64_b32 v[214:215], v4 offset0:17 offset1:19
	ds_read2st64_b32 v[216:217], v4 offset0:21 offset1:23
	ds_read2st64_b32 v[106:107], v5 offset0:1 offset1:3
	ds_read2st64_b32 v[108:109], v5 offset0:5 offset1:7
	ds_read2st64_b32 v[110:111], v5 offset0:17 offset1:19
	ds_read2st64_b32 v[112:113], v5 offset0:21 offset1:23
	v_pk_mul_f32 v[194:195], v[194:195], v[186:187]
	v_pk_mul_f32 v[196:197], v[196:197], v[188:189]
	v_pk_mul_f32 v[198:199], v[198:199], v[190:191]
	v_pk_mul_f32 v[200:201], v[200:201], v[192:193]
	v_cvt_pk_bf16_f32 v30, v194, v195
	v_cvt_pk_bf16_f32 v31, v196, v197
	v_cvt_pk_bf16_f32 v32, v198, v199
	v_cvt_pk_bf16_f32 v33, v200, v201
	v_add_u32_e32 v6, 0xa000, v9
	buffer_store_dwordx4 v[30:33], v6, s[72:75], 0 offen sc1
	s_waitcnt lgkmcnt(8)
	v_pk_mul_f32 v[202:203], v[202:203], v[186:187]
	v_pk_mul_f32 v[204:205], v[204:205], v[188:189]
	v_pk_mul_f32 v[206:207], v[206:207], v[190:191]
	v_pk_mul_f32 v[208:209], v[208:209], v[192:193]
	v_cvt_pk_bf16_f32 v114, v202, v203
	v_cvt_pk_bf16_f32 v115, v204, v205
	v_cvt_pk_bf16_f32 v116, v206, v207
	v_cvt_pk_bf16_f32 v117, v208, v209
	v_add_u32_e32 v7, 0xb000, v9
	buffer_store_dwordx4 v[114:117], v7, s[72:75], 0 offen sc1
	s_waitcnt lgkmcnt(4)
	v_pk_mul_f32 v[210:211], v[210:211], v[186:187]
	v_pk_mul_f32 v[212:213], v[212:213], v[188:189]
	v_pk_mul_f32 v[214:215], v[214:215], v[190:191]
	v_pk_mul_f32 v[216:217], v[216:217], v[192:193]
	v_cvt_pk_bf16_f32 v118, v210, v211
	v_cvt_pk_bf16_f32 v119, v212, v213
	v_cvt_pk_bf16_f32 v120, v214, v215
	v_cvt_pk_bf16_f32 v121, v216, v217
	v_add_u32_e32 v6, 0xc000, v9
	buffer_store_dwordx4 v[118:121], v6, s[72:75], 0 offen sc1
	s_waitcnt lgkmcnt(0)
	v_pk_mul_f32 v[106:107], v[106:107], v[186:187]
	v_pk_mul_f32 v[108:109], v[108:109], v[188:189]
	v_pk_mul_f32 v[110:111], v[110:111], v[190:191]
	v_pk_mul_f32 v[112:113], v[112:113], v[192:193]
	v_cvt_pk_bf16_f32 v122, v106, v107
	v_cvt_pk_bf16_f32 v123, v108, v109
	v_cvt_pk_bf16_f32 v124, v110, v111
	v_cvt_pk_bf16_f32 v125, v112, v113
	v_add_u32_e32 v7, 0xd000, v9
	buffer_store_dwordx4 v[122:125], v7, s[72:75], 0 offen sc1
